# MLA: speculative softmax of first key half in QK k2=1 MFMA gaps, PV starts right after the max check
# baseline (speedup 1.0000x reference)
; #define MFMA(a, b, c) __builtin_amdgcn_mfma_f32_32x32x16_bf16((a), (b), (c), 0, 0, 0)
; DEV float fast_exp2(float x) { return __builtin_amdgcn_exp2f(x); }
; DEV int crow_of(int reg, int h) { return (reg & 3) + 8 * (reg >> 2) + 4 * h; }
; template <int DQK, int DV, int NKH, int MODE>
; DEV void flash_unit(const FlashArgs& fa, char* smem, f32x16 (&oacc)[DV / 32], float& linv_out) {
;     ...
;       for (int k2 = 0; k2 < 2; ++k2) {
; #pragma unroll
;         for (int s = 0; s < NS; ++s) {
;           const bf16x8 kf = kfr[k2][s];
;           if (s == 0) st[k2] = MFMA(kf, qf[s], negm);
;           else st[k2] = MFMA(kf, qf[s], st[k2]);
;           constexpr int NQK = 2 * NS, EVERY = NQK / LPT;
;           const int m = k2 * NS + s;
;           if ((m + 1) % EVERY == 0 && (m + 1) / EVERY <= LPT) {
;             __builtin_amdgcn_sched_barrier(0);
;             if (pre) issue_piece(it + 3, (m + 1) / EVERY - 1);
;             __builtin_amdgcn_sched_barrier(0);
;           }
;         }
;       }
;       if (MODE == 1 && it >= 4) {
;         const int dr = krow - na_row + 7;
;         const float* bp = rpbs + dr * 31;
; #pragma unroll
;         for (int k2 = 0; k2 < 2; ++k2)
; #pragma unroll
;           for (int e = 0; e < 16; ++e) {
;             const int kc = k2 * 32 + crow_of(e, h);
;             const bool valid = (kc >= na_cstart) && (kc < na_cstart + 16);
;             const int idx = min(max(kc - na_qc + 15, 0), 30);
;             const float bv = bp[idx];
;             st[k2][e] = valid ? st[k2][e] + bv : -1e30f;
;           }
;       }
;       float rel = st[0][0];
; #pragma unroll
;       for (int e = 1; e < 16; ++e) rel = fmaxf(rel, st[0][e]);
; #pragma unroll
;       for (int e = 0; e < 16; ++e) rel = fmaxf(rel, st[1][e]);
;       rel = half_max(rel);
;       const bool first = (it == 0);
;       if (first || __builtin_amdgcn_ballot_w64(rel > 8.f) != 0) {
;         const float d = first ? rel : fmaxf(rel, 0.f);
;         const float alpha = fast_exp2(-d);
;         mrun += d;
; #pragma unroll
;         for (int k2 = 0; k2 < 2; ++k2)
; #pragma unroll
;           for (int e = 0; e < 16; ++e) st[k2][e] -= d;
; #pragma unroll
;         for (int v = 0; v < NV; ++v)
; #pragma unroll
;           for (int e = 0; e < 16; ++e) oacc[v][e] *= alpha;
; #pragma unroll
;         for (int e = 0; e < 16; ++e) negm[e] = -mrun;
;         lrun *= alpha;
;       }
.Lmla_d2:
	v_add3_u32 v122, s6, v156, v158
	v_add3_u32 v123, s6, v157, v158
	v_mfma_f32_32x32x16_bf16 v[48:63], v[104:107], v[88:91], v[48:63]
	ds_read_b64_tr_b16 v[104:105], v122 offset:12288
	ds_read_b64_tr_b16 v[106:107], v122 offset:13312
	v_mfma_f32_32x32x16_bf16 v[48:63], v[108:111], v[92:95], v[48:63]
	ds_read_b64_tr_b16 v[108:109], v123 offset:12288
	ds_read_b64_tr_b16 v[110:111], v123 offset:13312
	v_exp_f32_e32 v244, v64
	v_exp_f32_e32 v245, v65
	v_exp_f32_e32 v246, v66
	v_exp_f32_e32 v247, v67
	v_exp_f32_e32 v248, v68
	v_exp_f32_e32 v249, v69
	v_exp_f32_e32 v250, v70
	v_exp_f32_e32 v251, v71
	v_mfma_f32_32x32x16_bf16 v[48:63], v[112:115], v[96:99], v[48:63]
	ds_read_b64_tr_b16 v[112:113], v122 offset:14336
	ds_read_b64_tr_b16 v[114:115], v122 offset:15360
	v_exp_f32_e32 v252, v72
	v_exp_f32_e32 v253, v73
	v_exp_f32_e32 v254, v74
	v_exp_f32_e32 v255, v75
	v_exp_f32_e32 v160, v76
	v_exp_f32_e32 v161, v77
	v_exp_f32_e32 v162, v78
	v_exp_f32_e32 v163, v79
	v_add_f32_e32 v120, v244, v245
	v_add_f32_e32 v120, v120, v246
	v_add_f32_e32 v120, v120, v247
	v_mfma_f32_32x32x16_bf16 v[48:63], v[116:119], v[100:103], v[48:63]
	ds_read_b64_tr_b16 v[116:117], v123 offset:14336
	ds_read_b64_tr_b16 v[118:119], v123 offset:15360
	v_add_f32_e32 v120, v120, v248
	v_add_f32_e32 v120, v120, v249
	v_add_f32_e32 v120, v120, v250
	v_add_f32_e32 v120, v120, v251
	v_add_f32_e32 v120, v120, v252
	v_add_f32_e32 v120, v120, v253
	v_add_f32_e32 v120, v120, v254
	v_add_f32_e32 v120, v120, v255
	v_add_f32_e32 v120, v120, v160
	v_add_f32_e32 v120, v120, v161
	v_add_f32_e32 v120, v120, v162
	v_add_f32_e32 v120, v120, v163
	v_cvt_pk_bf16_f32 v244, v244, v245
	v_cvt_pk_bf16_f32 v245, v246, v247
	v_cvt_pk_bf16_f32 v246, v248, v249
	v_cvt_pk_bf16_f32 v247, v250, v251
	v_cvt_pk_bf16_f32 v252, v252, v253
	v_cvt_pk_bf16_f32 v253, v254, v255
	v_cvt_pk_bf16_f32 v254, v160, v161
	v_cvt_pk_bf16_f32 v255, v162, v163
	s_cmp_ge_u32 s19, s18
	s_cbranch_scc1 .Lmla_d3
	s_and_b64 vcc, exec, s[38:39]
	s_cbranch_vccnz .Lmla_d3
	s_add_i32 m0, s7, 0x4000
	s_nop 0
	global_load_lds_dwordx4 v[136:137], off
.Lmla_d3:
	v_max3_f32 v124, v64, v65, v66
	v_max3_f32 v125, v67, v68, v69
	v_max3_f32 v126, v70, v71, v72
	v_max3_f32 v127, v73, v74, v75
	v_max3_f32 v124, v124, v76, v77
	v_max3_f32 v125, v125, v78, v79
	v_max3_f32 v126, v126, v48, v49
	v_max3_f32 v127, v127, v50, v51
	v_max3_f32 v124, v124, v52, v53
	v_max3_f32 v125, v125, v54, v55
	v_max3_f32 v126, v126, v56, v57
	v_max3_f32 v127, v127, v58, v59
	v_max3_f32 v124, v124, v60, v61
	v_max3_f32 v125, v125, v62, v63
	v_max3_f32 v124, v124, v125, v126
	v_max_f32_e32 v124, v124, v127
	v_cmp_lt_f32_e32 vcc, s33, v124
	s_cbranch_vccz .Lmla_pv
	v_mov_b32_e32 v121, v124
	s_nop 1
	v_permlane32_swap_b32_e32 v124, v121
	v_max_f32_e32 v124, v124, v121
	v_max_f32_e32 v32, 0, v124
	v_exp_f32_e64 v34, -v32
	v_add_f32_e32 v135, v135, v32
	v_pk_add_f32 v[64:65], v[64:65], v[32:33] op_sel_hi:[1,0] neg_lo:[0,1] neg_hi:[0,1]
	v_pk_add_f32 v[66:67], v[66:67], v[32:33] op_sel_hi:[1,0] neg_lo:[0,1] neg_hi:[0,1]
	v_pk_add_f32 v[68:69], v[68:69], v[32:33] op_sel_hi:[1,0] neg_lo:[0,1] neg_hi:[0,1]
	v_pk_add_f32 v[70:71], v[70:71], v[32:33] op_sel_hi:[1,0] neg_lo:[0,1] neg_hi:[0,1]
	v_pk_add_f32 v[72:73], v[72:73], v[32:33] op_sel_hi:[1,0] neg_lo:[0,1] neg_hi:[0,1]
	v_pk_add_f32 v[74:75], v[74:75], v[32:33] op_sel_hi:[1,0] neg_lo:[0,1] neg_hi:[0,1]
	v_pk_add_f32 v[76:77], v[76:77], v[32:33] op_sel_hi:[1,0] neg_lo:[0,1] neg_hi:[0,1]
	v_pk_add_f32 v[78:79], v[78:79], v[32:33] op_sel_hi:[1,0] neg_lo:[0,1] neg_hi:[0,1]
	v_pk_add_f32 v[48:49], v[48:49], v[32:33] op_sel_hi:[1,0] neg_lo:[0,1] neg_hi:[0,1]
	v_pk_add_f32 v[50:51], v[50:51], v[32:33] op_sel_hi:[1,0] neg_lo:[0,1] neg_hi:[0,1]
	v_pk_add_f32 v[52:53], v[52:53], v[32:33] op_sel_hi:[1,0] neg_lo:[0,1] neg_hi:[0,1]
	v_pk_add_f32 v[54:55], v[54:55], v[32:33] op_sel_hi:[1,0] neg_lo:[0,1] neg_hi:[0,1]
	v_pk_add_f32 v[56:57], v[56:57], v[32:33] op_sel_hi:[1,0] neg_lo:[0,1] neg_hi:[0,1]
	v_pk_add_f32 v[58:59], v[58:59], v[32:33] op_sel_hi:[1,0] neg_lo:[0,1] neg_hi:[0,1]
	v_pk_add_f32 v[60:61], v[60:61], v[32:33] op_sel_hi:[1,0] neg_lo:[0,1] neg_hi:[0,1]
	v_pk_add_f32 v[62:63], v[62:63], v[32:33] op_sel_hi:[1,0] neg_lo:[0,1] neg_hi:[0,1]
	v_xor_b32_e32 v32, 0x80000000, v135
	v_pk_mul_f32 v[14:15], v[14:15], v[34:35] op_sel_hi:[1,0]
	v_pk_mul_f32 v[12:13], v[12:13], v[34:35] op_sel_hi:[1,0]
	v_pk_mul_f32 v[10:11], v[10:11], v[34:35] op_sel_hi:[1,0]
	v_pk_mul_f32 v[8:9], v[8:9], v[34:35] op_sel_hi:[1,0]
	v_pk_mul_f32 v[6:7], v[6:7], v[34:35] op_sel_hi:[1,0]
	v_pk_mul_f32 v[4:5], v[4:5], v[34:35] op_sel_hi:[1,0]
	v_pk_mul_f32 v[2:3], v[2:3], v[34:35] op_sel_hi:[1,0]
	v_pk_mul_f32 v[0:1], v[0:1], v[34:35] op_sel_hi:[1,0]
	v_pk_mul_f32 v[30:31], v[30:31], v[34:35] op_sel_hi:[1,0]
	v_pk_mul_f32 v[28:29], v[28:29], v[34:35] op_sel_hi:[1,0]
	v_pk_mul_f32 v[26:27], v[26:27], v[34:35] op_sel_hi:[1,0]
	v_pk_mul_f32 v[24:25], v[24:25], v[34:35] op_sel_hi:[1,0]
	v_pk_mul_f32 v[22:23], v[22:23], v[34:35] op_sel_hi:[1,0]
	v_pk_mul_f32 v[20:21], v[20:21], v[34:35] op_sel_hi:[1,0]
	v_pk_mul_f32 v[18:19], v[18:19], v[34:35] op_sel_hi:[1,0]
	v_pk_mul_f32 v[16:17], v[16:17], v[34:35] op_sel_hi:[1,0]
	v_mul_f32_e32 v134, v134, v34
	v_mov_b32_e32 v33, v32
	v_mov_b32_e32 v34, v32
	v_mov_b32_e32 v35, v32
	v_mov_b32_e32 v36, v32
	v_mov_b32_e32 v37, v32
	v_mov_b32_e32 v38, v32
	v_mov_b32_e32 v39, v32
	v_mov_b32_e32 v40, v32
	v_mov_b32_e32 v41, v32
	v_mov_b32_e32 v42, v32
	v_mov_b32_e32 v43, v32
	v_mov_b32_e32 v44, v32
	v_mov_b32_e32 v45, v32
	v_mov_b32_e32 v46, v32
	v_mov_b32_e32 v47, v32
	s_branch .LBB0_170
; #define MFMA(a, b, c) __builtin_amdgcn_mfma_f32_32x32x16_bf16((a), (b), (c), 0, 0, 0)
; DEV float fast_exp2(float x) { return __builtin_amdgcn_exp2f(x); }
; template <int DQK, int DV, int NKH, int MODE>
; DEV void flash_unit(const FlashArgs& fa, char* smem, f32x16 (&oacc)[DV / 32], float& linv_out) {
;     ...
;       float psum = 0.f;
; #pragma unroll
;       for (int k2 = 0; k2 < 2; ++k2)
; #pragma unroll
;         for (int e = 0; e < 16; ++e) { st[k2][e] = fast_exp2(st[k2][e]); psum += st[k2][e]; }
;       lrun += psum;
;       bf16x8 pf[2][2];
; #pragma unroll
;       for (int k2 = 0; k2 < 2; ++k2)
; #pragma unroll
;         for (int s2 = 0; s2 < 2; ++s2) {
;           uint4 u = make_uint4(pk2(st[k2][8 * s2], st[k2][8 * s2 + 1]), pk2(st[k2][8 * s2 + 2], st[k2][8 * s2 + 3]),
;                                pk2(st[k2][8 * s2 + 4], st[k2][8 * s2 + 5]), pk2(st[k2][8 * s2 + 6], st[k2][8 * s2 + 7]));
;           pf[k2][s2] = __builtin_bit_cast(bf16x8, u);
;         }
; #pragma unroll
;       for (int v = 0; v < NV; ++v)
; #pragma unroll
;         for (int k2 = 0; k2 < 2; ++k2)
; #pragma unroll
;           for (int s2 = 0; s2 < 2; ++s2) {
;             const char* a1 = vb + (k2 * 32 + s2 * 16) * VROW + vhi[v] + vlow0;
;             const char* a2 = vb + (k2 * 32 + s2 * 16 + 8) * VROW + vhi[v] + vlow1;
;             s16x4 lo = __builtin_amdgcn_ds_read_tr16_b64_v4i16((__attribute__((address_space(3))) s16x4*)(a1));
;             s16x4 hi = __builtin_amdgcn_ds_read_tr16_b64_v4i16((__attribute__((address_space(3))) s16x4*)(a2));
;             const bf16x8 vf = __builtin_shufflevector(lo, hi, 0, 1, 2, 3, 4, 5, 6, 7);
;             oacc[v] = MFMA(vf, pf[k2][s2], oacc[v]);
;           }
.Lmla_pv:
	s_waitcnt lgkmcnt(6)
	v_mfma_f32_32x32x16_bf16 v[16:31], v[104:107], v[244:247], v[16:31]
	v_exp_f32_e32 v48, v48
	v_exp_f32_e32 v49, v49
	v_exp_f32_e32 v50, v50
	v_exp_f32_e32 v51, v51
	ds_read_b64_tr_b16 v[104:105], v122 offset:16384
	v_add_f32_e32 v120, v120, v48
	v_add_f32_e32 v120, v120, v49
	v_cvt_pk_bf16_f32 v48, v48, v49
	ds_read_b64_tr_b16 v[106:107], v122 offset:17408
	v_add_f32_e32 v120, v120, v50
	v_cvt_pk_bf16_f32 v49, v50, v51
	v_add_f32_e32 v120, v120, v51
	s_waitcnt lgkmcnt(6)
	v_mfma_f32_32x32x16_bf16 v[0:15], v[108:111], v[244:247], v[0:15]
	v_exp_f32_e32 v52, v52
	v_exp_f32_e32 v53, v53
	v_exp_f32_e32 v54, v54
	v_exp_f32_e32 v55, v55
	ds_read_b64_tr_b16 v[108:109], v123 offset:16384
	v_add_f32_e32 v120, v120, v52
	v_add_f32_e32 v120, v120, v53
	v_cvt_pk_bf16_f32 v50, v52, v53
	ds_read_b64_tr_b16 v[110:111], v123 offset:17408
	v_add_f32_e32 v120, v120, v54
	v_cvt_pk_bf16_f32 v51, v54, v55
	v_add_f32_e32 v120, v120, v55
	s_waitcnt lgkmcnt(6)
	v_mfma_f32_32x32x16_bf16 v[16:31], v[112:115], v[252:255], v[16:31]
	v_exp_f32_e32 v56, v56
	v_exp_f32_e32 v57, v57
	v_exp_f32_e32 v58, v58
	v_exp_f32_e32 v59, v59
	ds_read_b64_tr_b16 v[112:113], v122 offset:18432
	v_add_f32_e32 v120, v120, v56
	v_add_f32_e32 v120, v120, v57
	v_cvt_pk_bf16_f32 v56, v56, v57
	ds_read_b64_tr_b16 v[114:115], v122 offset:19456
	v_add_f32_e32 v120, v120, v58
	v_cvt_pk_bf16_f32 v57, v58, v59
	v_add_f32_e32 v120, v120, v59
	s_waitcnt lgkmcnt(6)
	v_mfma_f32_32x32x16_bf16 v[0:15], v[116:119], v[252:255], v[0:15]
	v_exp_f32_e32 v60, v60
	v_exp_f32_e32 v61, v61
	v_exp_f32_e32 v62, v62
	v_exp_f32_e32 v63, v63
	ds_read_b64_tr_b16 v[116:117], v123 offset:18432
	v_add_f32_e32 v120, v120, v60
	v_add_f32_e32 v120, v120, v61
	v_cvt_pk_bf16_f32 v58, v60, v61
	ds_read_b64_tr_b16 v[118:119], v123 offset:19456
	v_add_f32_e32 v120, v120, v62
	v_cvt_pk_bf16_f32 v59, v62, v63
	v_add_f32_e32 v120, v120, v63
	s_waitcnt lgkmcnt(6)
	v_mfma_f32_32x32x16_bf16 v[16:31], v[104:107], v[48:51], v[16:31]
	v_add_f32_e32 v134, v134, v120
	s_waitcnt lgkmcnt(4)
	v_mfma_f32_32x32x16_bf16 v[0:15], v[108:111], v[48:51], v[0:15]
	v_lshl_add_u64 v[136:137], v[136:137], 0, v[132:133]
	v_lshl_add_u64 v[138:139], v[138:139], 0, v[130:131]
	s_waitcnt lgkmcnt(2)
	v_mfma_f32_32x32x16_bf16 v[16:31], v[112:115], v[56:59], v[16:31]
	v_lshl_add_u64 v[140:141], v[140:141], 0, v[128:129]
	s_add_i32 s20, s20, -1
	s_add_i32 s19, s19, 1
	s_waitcnt lgkmcnt(0)
	v_mfma_f32_32x32x16_bf16 v[0:15], v[116:119], v[56:59], v[0:15]
	s_cmp_lg_u32 s20, -1
	s_cbranch_scc1 .LBB0_171
	s_branch .LBB0_128
